# P9 residual epilogue de-serialised: gate vectors loaded once per tile, residual loads 8 deep with counted vmcnt (was 32 x load-load-wait0-fma-store)
# baseline (speedup 1.0000x reference)
; #define LAUNDER_GPTR(p) do { p = launder_gptr(p); } while (0)
;     __device__ __forceinline__ void operator()(const f32x4 (&acc)[2][2][4][2], const Unit& u, int wr, int wc, int fr, int fq) const {
;         unsigned char* ws = P->ws; LAUNDER_GPTR(ws);
;         const float* MOD = (const float*)(ws + WS_MOD);
;         float* X1 = (float*)(ws + WS_X1);
;         const int col0 = u.pn * 256 + wc * 32 + 8 * fq;
; #pragma unroll
;         for (int ai = 0; ai < 2; ++ai)
; #pragma unroll
;             for (int m = 0; m < 4; ++m) {
;                 const int r = u.pm * 256 + ai * 128 + wr * 64 + m * 16 + fr;
;                 const float* gate = MOD + (size_t)mod_row(r) * 6144 + (WHICH == 0 ? 2048 : 5120) + col0;
;                 const float* res = (WHICH == 0) ? (r < NPR ? P->in[0] + (size_t)r * DM : P->in[1] + (size_t)(r - NPR) * DM) + col0 : X1 + (size_t)r * DM + col0;
;                 float* dst = (WHICH == 0) ? X1 + (size_t)r * DM + col0 : P->out + (size_t)r * DM + col0;
; #pragma unroll
;                 for (int bj = 0; bj < 2; ++bj)
; #pragma unroll
;                     for (int n = 0; n < 2; ++n) { const int o = bj * 128 + 4 * n;
;                         const f32x4 g = *(const f32x4*)(gate + o), x = *(const f32x4*)(res + o);
;                         *(f32x4*)(dst + o) = x + g * acc[ai][bj][m][n]; }
;             }
;     }
.LBB0_1943:
	s_lshl_b32 s24, s53, 8
	s_add_i32 s24, s24, s44
	v_or_b32_e32 v150, s24, v152
	v_add_u32_e32 v148, 0xffffc000, v150
	v_lshl_or_b32 v144, s54, 8, v154
	s_ashr_i32 s25, s24, 13
	v_lshrrev_b32_e32 v148, 2, v148
	s_mov_b64 s[26:27], s[10:11]
	v_ashrrev_i32_e32 v145, 31, v144
	v_add_u32_e32 v148, 2, v148
	v_mov_b32_e32 v172, s25
	v_cmp_gt_i32_e32 vcc, s42, v150
	v_lshlrev_b64 v[144:145], 2, v[144:145]
	v_lshl_add_u64 v[146:147], s[26:27], 0, v[144:145]
	v_cndmask_b32_e32 v151, v148, v172, vcc
	v_mov_b64_e32 v[148:149], s[26:27]
	v_mad_i64_i32 v[158:159], s[26:27], v151, s43, v[148:149]
	v_lshl_add_u64 v[166:167], v[158:159], 0, v[144:145]
	v_ashrrev_i32_e32 v151, 31, v150
	v_add_co_u32_e32 v158, vcc, s50, v166
	v_lshl_add_u64 v[146:147], v[146:147], 0, s[18:19]
	v_lshlrev_b64 v[168:169], 12, v[150:151]
	v_addc_co_u32_e32 v159, vcc, 0, v167, vcc
	v_lshl_add_u64 v[170:171], v[146:147], 0, v[168:169]
	s_nop 0
	v_lshl_add_u64 v[168:169], s[8:9], 0, v[168:169]
	v_lshl_add_u64 v[168:169], v[168:169], 0, v[144:145]
	v_lshl_add_u64 v[166:167], v[166:167], 0, s[20:21]
	s_addk_i32 s24, 0x80
	v_readfirstlane_b32 s98, v170
	v_readfirstlane_b32 s99, v171
	v_readfirstlane_b32 s100, v168
	v_readfirstlane_b32 s101, v169
	global_load_dwordx4 v[172:175], v[166:167], off offset:0
	global_load_dwordx4 v[176:179], v[166:167], off offset:16
	global_load_dwordx4 v[180:183], v[166:167], off offset:512
	global_load_dwordx4 v[184:187], v[166:167], off offset:528
	v_subrev_u32_e32 v144, s98, v170
	v_add_u32_e32 v145, 0x10000, v144
	v_add_u32_e32 v146, 0x20000, v144
	v_add_u32_e32 v147, 0x30000, v144
	v_add_u32_e32 v148, 0x80000, v144
	v_add_u32_e32 v149, 0x90000, v144
	v_add_u32_e32 v150, 0xa0000, v144
	v_add_u32_e32 v151, 0xb0000, v144
	global_load_dwordx4 v[188:191], v144, s[98:99] offset:0
	global_load_dwordx4 v[192:195], v144, s[98:99] offset:16
	global_load_dwordx4 v[196:199], v144, s[98:99] offset:512
	global_load_dwordx4 v[200:203], v144, s[98:99] offset:528
	global_load_dwordx4 v[204:207], v145, s[98:99] offset:0
	global_load_dwordx4 v[208:211], v145, s[98:99] offset:16
	global_load_dwordx4 v[158:161], v145, s[98:99] offset:512
	global_load_dwordx4 v[162:165], v145, s[98:99] offset:528
	s_waitcnt vmcnt(7)
	v_pk_fma_f32 v[124:125], v[124:125], v[172:173], v[188:189]
	v_pk_fma_f32 v[126:127], v[126:127], v[174:175], v[190:191]
	global_store_dwordx4 v144, v[124:127], s[100:101] offset:0
	global_load_dwordx4 v[188:191], v146, s[98:99] offset:0
	s_waitcnt vmcnt(8)
	v_pk_fma_f32 v[120:121], v[120:121], v[176:177], v[192:193]
	v_pk_fma_f32 v[122:123], v[122:123], v[178:179], v[194:195]
	global_store_dwordx4 v144, v[120:123], s[100:101] offset:16
	global_load_dwordx4 v[192:195], v146, s[98:99] offset:16
	s_waitcnt vmcnt(9)
	v_pk_fma_f32 v[116:117], v[116:117], v[180:181], v[196:197]
	v_pk_fma_f32 v[118:119], v[118:119], v[182:183], v[198:199]
	global_store_dwordx4 v144, v[116:119], s[100:101] offset:512
	global_load_dwordx4 v[196:199], v146, s[98:99] offset:512
	s_waitcnt vmcnt(10)
	v_pk_fma_f32 v[108:109], v[108:109], v[184:185], v[200:201]
	v_pk_fma_f32 v[110:111], v[110:111], v[186:187], v[202:203]
	global_store_dwordx4 v144, v[108:111], s[100:101] offset:528
	global_load_dwordx4 v[200:203], v146, s[98:99] offset:528
	s_waitcnt vmcnt(11)
	v_pk_fma_f32 v[112:113], v[112:113], v[172:173], v[204:205]
	v_pk_fma_f32 v[114:115], v[114:115], v[174:175], v[206:207]
	global_store_dwordx4 v145, v[112:115], s[100:101] offset:0
	global_load_dwordx4 v[204:207], v147, s[98:99] offset:0
	s_waitcnt vmcnt(12)
	v_pk_fma_f32 v[104:105], v[104:105], v[176:177], v[208:209]
	v_pk_fma_f32 v[106:107], v[106:107], v[178:179], v[210:211]
	global_store_dwordx4 v145, v[104:107], s[100:101] offset:16
	global_load_dwordx4 v[208:211], v147, s[98:99] offset:16
	s_waitcnt vmcnt(13)
	v_pk_fma_f32 v[100:101], v[100:101], v[180:181], v[158:159]
	v_pk_fma_f32 v[102:103], v[102:103], v[182:183], v[160:161]
	global_store_dwordx4 v145, v[100:103], s[100:101] offset:512
	global_load_dwordx4 v[158:161], v147, s[98:99] offset:512
	s_waitcnt vmcnt(14)
	v_pk_fma_f32 v[92:93], v[92:93], v[184:185], v[162:163]
	v_pk_fma_f32 v[94:95], v[94:95], v[186:187], v[164:165]
	global_store_dwordx4 v145, v[92:95], s[100:101] offset:528
	global_load_dwordx4 v[162:165], v147, s[98:99] offset:528
	s_waitcnt vmcnt(14)
	v_pk_fma_f32 v[96:97], v[96:97], v[172:173], v[188:189]
	v_pk_fma_f32 v[98:99], v[98:99], v[174:175], v[190:191]
	global_store_dwordx4 v146, v[96:99], s[100:101] offset:0
	global_load_dwordx4 v[188:191], v148, s[98:99] offset:0
	s_waitcnt vmcnt(14)
	v_pk_fma_f32 v[88:89], v[88:89], v[176:177], v[192:193]
	v_pk_fma_f32 v[90:91], v[90:91], v[178:179], v[194:195]
	global_store_dwordx4 v146, v[88:91], s[100:101] offset:16
	global_load_dwordx4 v[192:195], v148, s[98:99] offset:16
	s_waitcnt vmcnt(14)
	v_pk_fma_f32 v[84:85], v[84:85], v[180:181], v[196:197]
	v_pk_fma_f32 v[86:87], v[86:87], v[182:183], v[198:199]
	global_store_dwordx4 v146, v[84:87], s[100:101] offset:512
	global_load_dwordx4 v[196:199], v148, s[98:99] offset:512
	s_waitcnt vmcnt(14)
;     __device__ __forceinline__ void operator()(const f32x4 (&acc)[2][2][4][2], const Unit& u, int wr, int wc, int fr, int fq) const {
;     ...
;                 const float* res = (WHICH == 0) ? (r < NPR ? P->in[0] + (size_t)r * DM : P->in[1] + (size_t)(r - NPR) * DM) + col0 : X1 + (size_t)r * DM + col0;
;                 float* dst = (WHICH == 0) ? X1 + (size_t)r * DM + col0 : P->out + (size_t)r * DM + col0;
; #pragma unroll
;                 for (int bj = 0; bj < 2; ++bj)
; #pragma unroll
;                     for (int n = 0; n < 2; ++n) { const int o = bj * 128 + 4 * n;
;                         const f32x4 g = *(const f32x4*)(gate + o), x = *(const f32x4*)(res + o);
;                         *(f32x4*)(dst + o) = x + g * acc[ai][bj][m][n]; }
	v_pk_fma_f32 v[76:77], v[76:77], v[184:185], v[200:201]
	v_pk_fma_f32 v[78:79], v[78:79], v[186:187], v[202:203]
	global_store_dwordx4 v146, v[76:79], s[100:101] offset:528
	global_load_dwordx4 v[200:203], v148, s[98:99] offset:528
	s_waitcnt vmcnt(14)
	v_pk_fma_f32 v[80:81], v[80:81], v[172:173], v[204:205]
	v_pk_fma_f32 v[82:83], v[82:83], v[174:175], v[206:207]
	global_store_dwordx4 v147, v[80:83], s[100:101] offset:0
	global_load_dwordx4 v[204:207], v149, s[98:99] offset:0
	s_waitcnt vmcnt(14)
	v_pk_fma_f32 v[72:73], v[72:73], v[176:177], v[208:209]
	v_pk_fma_f32 v[74:75], v[74:75], v[178:179], v[210:211]
	global_store_dwordx4 v147, v[72:75], s[100:101] offset:16
	global_load_dwordx4 v[208:211], v149, s[98:99] offset:16
	s_waitcnt vmcnt(14)
	v_pk_fma_f32 v[68:69], v[68:69], v[180:181], v[158:159]
	v_pk_fma_f32 v[70:71], v[70:71], v[182:183], v[160:161]
	global_store_dwordx4 v147, v[68:71], s[100:101] offset:512
	global_load_dwordx4 v[158:161], v149, s[98:99] offset:512
	s_waitcnt vmcnt(14)
	v_pk_fma_f32 v[64:65], v[64:65], v[184:185], v[162:163]
	v_pk_fma_f32 v[66:67], v[66:67], v[186:187], v[164:165]
	global_store_dwordx4 v147, v[64:67], s[100:101] offset:528
	global_load_dwordx4 v[162:165], v149, s[98:99] offset:528
	s_waitcnt vmcnt(14)
	v_pk_fma_f32 v[60:61], v[60:61], v[172:173], v[188:189]
	v_pk_fma_f32 v[62:63], v[62:63], v[174:175], v[190:191]
	global_store_dwordx4 v148, v[60:63], s[100:101] offset:0
	global_load_dwordx4 v[188:191], v150, s[98:99] offset:0
	s_waitcnt vmcnt(14)
	v_pk_fma_f32 v[56:57], v[56:57], v[176:177], v[192:193]
	v_pk_fma_f32 v[58:59], v[58:59], v[178:179], v[194:195]
	global_store_dwordx4 v148, v[56:59], s[100:101] offset:16
	global_load_dwordx4 v[192:195], v150, s[98:99] offset:16
	s_waitcnt vmcnt(14)
	v_pk_fma_f32 v[52:53], v[52:53], v[180:181], v[196:197]
	v_pk_fma_f32 v[54:55], v[54:55], v[182:183], v[198:199]
	global_store_dwordx4 v148, v[52:55], s[100:101] offset:512
	global_load_dwordx4 v[196:199], v150, s[98:99] offset:512
	s_waitcnt vmcnt(14)
	v_pk_fma_f32 v[44:45], v[44:45], v[184:185], v[200:201]
	v_pk_fma_f32 v[46:47], v[46:47], v[186:187], v[202:203]
	global_store_dwordx4 v148, v[44:47], s[100:101] offset:528
	global_load_dwordx4 v[200:203], v150, s[98:99] offset:528
	s_waitcnt vmcnt(14)
	v_pk_fma_f32 v[48:49], v[48:49], v[172:173], v[204:205]
	v_pk_fma_f32 v[50:51], v[50:51], v[174:175], v[206:207]
	global_store_dwordx4 v149, v[48:51], s[100:101] offset:0
	global_load_dwordx4 v[204:207], v151, s[98:99] offset:0
	s_waitcnt vmcnt(14)
	v_pk_fma_f32 v[40:41], v[40:41], v[176:177], v[208:209]
	v_pk_fma_f32 v[42:43], v[42:43], v[178:179], v[210:211]
	global_store_dwordx4 v149, v[40:43], s[100:101] offset:16
	global_load_dwordx4 v[208:211], v151, s[98:99] offset:16
	s_waitcnt vmcnt(14)
	v_pk_fma_f32 v[36:37], v[36:37], v[180:181], v[158:159]
	v_pk_fma_f32 v[38:39], v[38:39], v[182:183], v[160:161]
	global_store_dwordx4 v149, v[36:39], s[100:101] offset:512
	global_load_dwordx4 v[158:161], v151, s[98:99] offset:512
	s_waitcnt vmcnt(14)
	v_pk_fma_f32 v[28:29], v[28:29], v[184:185], v[162:163]
	v_pk_fma_f32 v[30:31], v[30:31], v[186:187], v[164:165]
	global_store_dwordx4 v149, v[28:31], s[100:101] offset:528
	global_load_dwordx4 v[162:165], v151, s[98:99] offset:528
	s_waitcnt vmcnt(14)
	v_pk_fma_f32 v[32:33], v[32:33], v[172:173], v[188:189]
	v_pk_fma_f32 v[34:35], v[34:35], v[174:175], v[190:191]
	global_store_dwordx4 v150, v[32:35], s[100:101] offset:0
	s_waitcnt vmcnt(13)
	v_pk_fma_f32 v[24:25], v[24:25], v[176:177], v[192:193]
	v_pk_fma_f32 v[26:27], v[26:27], v[178:179], v[194:195]
	global_store_dwordx4 v150, v[24:27], s[100:101] offset:16
	s_waitcnt vmcnt(12)
	v_pk_fma_f32 v[20:21], v[20:21], v[180:181], v[196:197]
	v_pk_fma_f32 v[22:23], v[22:23], v[182:183], v[198:199]
	global_store_dwordx4 v150, v[20:23], s[100:101] offset:512
	s_waitcnt vmcnt(11)
	v_pk_fma_f32 v[12:13], v[12:13], v[184:185], v[200:201]
	v_pk_fma_f32 v[14:15], v[14:15], v[186:187], v[202:203]
	global_store_dwordx4 v150, v[12:15], s[100:101] offset:528
	s_waitcnt vmcnt(10)
	v_pk_fma_f32 v[16:17], v[16:17], v[172:173], v[204:205]
	v_pk_fma_f32 v[18:19], v[18:19], v[174:175], v[206:207]
	global_store_dwordx4 v151, v[16:19], s[100:101] offset:0
	s_waitcnt vmcnt(9)
	v_pk_fma_f32 v[8:9], v[8:9], v[176:177], v[208:209]
	v_pk_fma_f32 v[10:11], v[10:11], v[178:179], v[210:211]
	global_store_dwordx4 v151, v[8:11], s[100:101] offset:16
	s_waitcnt vmcnt(8)
	v_pk_fma_f32 v[4:5], v[4:5], v[180:181], v[158:159]
	v_pk_fma_f32 v[6:7], v[6:7], v[182:183], v[160:161]
	global_store_dwordx4 v151, v[4:7], s[100:101] offset:512
	s_waitcnt vmcnt(7)
	v_pk_fma_f32 v[0:1], v[0:1], v[184:185], v[162:163]
	v_pk_fma_f32 v[2:3], v[2:3], v[186:187], v[164:165]
	global_store_dwordx4 v151, v[0:3], s[100:101] offset:528
	s_and_b64 vcc, exec, s[2:3]
	s_mov_b64 s[2:3], -1
	s_cbranch_vccnz .LBB0_1928
	s_andn2_b64 vcc, exec, s[12:13]
	s_cbranch_vccnz .LBB0_1927
	s_barrier
	s_branch .LBB0_1927
